# merge phase: hoist loop-invariant out_g loads (8 x dwordx4, 4 serialized round trips per token) out of the token loop
# speedup vs baseline: 1.0224x; 1.0062x over previous
; __device__ __forceinline__ void merge_phase(unsigned char* ws_, unsigned char* outb, const float* outg_, int wg, int nwg, int grp, int tok0, int tokend, bf16_t* obuf) {
;     const int tid = fresh_tid(), lane = tid & 63, gw = wg * 8 + (tid >> 6), NGW = nwg * 8;
;     const int h = lane >> 2, q = lane & 3;
;     const float* outg = outg_ + h * 128 + q * 32;
;     for (int tok = tok0 + gw; tok < tokend; tok += NGW) {
;         float v[32];
;         if (h < 4) {
;             int pt_; const u32x4* sp = (const u32x4*)(scr_row(ws_, outb, grp, 3, tok, pt_) + h * 128 + q * 32);
; #pragma unroll
;             for (int c = 0; c < 4; ++c) { const u32x4 w = sp[c];
;                 v[8 * c + 0] = bf_lo(w.x); v[8 * c + 1] = bf_hi(w.x); v[8 * c + 2] = bf_lo(w.y); v[8 * c + 3] = bf_hi(w.y);
;                 v[8 * c + 4] = bf_lo(w.z); v[8 * c + 5] = bf_hi(w.z); v[8 * c + 6] = bf_lo(w.w); v[8 * c + 7] = bf_hi(w.w); }
;         } else {
;             const int hd = h - 4; const float* lse = (const float*)(ws_ + OFF_LSE);
;             const size_t gt = (size_t)grp * SEQ + tok;
;             const float l0 = lse[((size_t)0 * MTOK + gt) * 12 + hd], l1 = lse[((size_t)1 * MTOK + gt) * 12 + hd], l2 = lse[((size_t)2 * MTOK + gt) * 12 + hd];
;             const float mx = fmaxf(l0, fmaxf(l1, l2));
;             float w0 = __expf(l0 - mx), w1 = __expf(l1 - mx), w2 = __expf(l2 - mx);
;             const float inv = 1.0f / (w0 + w1 + w2); w0 *= inv; w1 *= inv; w2 *= inv;
; #pragma unroll
;             for (int i = 0; i < 32; ++i) v[i] = 0.f;
; #pragma unroll
;             for (int p = 0; p < 3; ++p) { const float wp = (p == 0) ? w0 : (p == 1 ? w1 : w2);
;                 int pt_; const u32x4* sp = (const u32x4*)(scr_row(ws_, outb, grp, p, tok, pt_) + hd * 128 + q * 32);
; #pragma unroll
;                 for (int c = 0; c < 4; ++c) { const u32x4 w = sp[c];
;                     v[8 * c + 0] += wp * bf_lo(w.x); v[8 * c + 1] += wp * bf_hi(w.x); v[8 * c + 2] += wp * bf_lo(w.y); v[8 * c + 3] += wp * bf_hi(w.y);
;                     v[8 * c + 4] += wp * bf_lo(w.z); v[8 * c + 5] += wp * bf_hi(w.z); v[8 * c + 6] += wp * bf_lo(w.w); v[8 * c + 7] += wp * bf_hi(w.w); } }
;         }
;         float ss = 0.f;
; #pragma unroll
;         for (int i = 0; i < 32; ++i) ss += v[i] * v[i];
;         ss += __shfl_xor(ss, 1); ss += __shfl_xor(ss, 2);
.LBB0_607:
	s_or_b64 exec, exec, s[2:3]
	s_waitcnt lgkmcnt(0)
	v_mov_b32_e32 v0, v158
	v_readlane_b32 s2, v232, 22
	s_barrier
	s_add_i32 s2, s61, s2
	v_ashrrev_i32_e32 v1, 6, v0
	s_add_i32 s10, s61, 0x800
	v_add_u32_e32 v12, s2, v1
	v_cmp_gt_i32_e32 vcc, s10, v12
	s_and_saveexec_b64 s[2:3], vcc
	s_cbranch_execz .LBB0_614
	s_load_dwordx2 s[4:5], s[0:1], 0x50
	s_load_dwordx2 s[8:9], s[0:1], 0xb0
	v_bfe_u32 v1, v0, 2, 4
	v_lshlrev_b32_e32 v3, 5, v0
	v_mov_b32_e32 v15, 0
	v_lshlrev_b32_e32 v14, 9, v1
	v_and_b32_e32 v6, 0x60, v3
	s_waitcnt lgkmcnt(0)
	v_lshl_add_u64 v[4:5], s[4:5], 0, v[14:15]
	v_lshlrev_b32_e32 v14, 2, v6
	v_mbcnt_hi_u32_b32 v3, -1, v159
	v_lshl_add_u64 v[16:17], v[4:5], 0, v[14:15]
	v_and_b32_e32 v5, 64, v3
	v_subrev_co_u32_e32 v14, vcc, 4, v1
	v_xor_b32_e32 v4, 1, v3
	v_add_u32_e32 v5, 64, v5
	s_xor_b64 s[4:5], vcc, -1
	v_cmp_lt_i32_e32 vcc, v4, v5
	v_readlane_b32 s27, v232, 0
	s_lshl_b32 s6, s27, 26
	v_cndmask_b32_e32 v4, v3, v4, vcc
	v_lshlrev_b32_e32 v52, 2, v4
	v_xor_b32_e32 v4, 2, v3
	s_add_u32 s6, s8, s6
	v_cmp_lt_i32_e32 vcc, v4, v5
	s_addc_u32 s7, s9, 0
	s_lshl_b32 s8, s67, 9
	v_cndmask_b32_e32 v3, v3, v4, vcc
	v_lshlrev_b32_e32 v53, 2, v3
	s_and_b32 s11, s8, 0xfffff000
	v_mad_i64_i32 v[4:5], s[8:9], v12, 48, 0
	v_mov_b32_e32 v3, 0x60000
	v_readlane_b32 s28, v232, 11
	s_lshl_b32 s22, s27, 25
	v_mad_u64_u32 v[4:5], s[8:9], s27, v3, v[4:5]
	s_ashr_i32 s27, s26, 31
	s_lshl_b32 s28, s28, 24
	v_readlane_b32 s29, v232, 10
	v_ashrrev_i32_e32 v13, 31, v12
	s_add_u32 s28, s29, s28
	v_lshl_add_u64 v[20:21], v[14:15], 2, v[4:5]
	s_addc_u32 s29, 0, 0
	v_lshlrev_b64 v[4:5], 12, v[12:13]
	v_lshlrev_b32_e32 v18, 7, v14
	v_lshl_add_u64 v[8:9], s[28:29], 0, v[4:5]
	v_lshlrev_b32_e32 v14, 8, v1
	v_lshlrev_b32_e32 v0, 6, v0
	v_lshl_add_u64 v[8:9], v[8:9], 0, v[14:15]
	v_and_b32_e32 v14, 0xc0, v0
	v_lshlrev_b32_e32 v2, 7, v1
	s_mov_b32 s23, 0
	v_lshl_add_u64 v[0:1], v[8:9], 0, v[14:15]
	s_mov_b64 s[28:29], 0x13b50020
	v_lshl_add_u64 v[22:23], v[0:1], 0, s[28:29]
	v_lshl_add_u64 v[0:1], s[22:23], 0, v[4:5]
	v_mov_b32_e32 v19, v15
	v_or_b32_e32 v0, v0, v14
	v_lshl_add_u64 v[0:1], v[18:19], 1, v[0:1]
	s_mov_b64 s[22:23], 0xfb50020
	v_lshlrev_b32_e32 v54, 9, v12
	s_mul_hi_i32 s9, s26, 48
	s_mul_i32 s8, s26, 48
	s_lshl_b64 s[30:31], s[26:27], 12
	v_lshl_add_u64 v[24:25], v[0:1], 0, s[22:23]
	s_mov_b64 s[34:35], 0
	s_mov_b64 s[38:39], 0x600000
	s_mov_b32 s22, 0x600000
	v_lshlrev_b32_e32 v26, 1, v2
	s_mov_b64 s[42:43], 0xc00000
	v_mov_b32_e32 v13, 0x358637bd
	v_lshlrev_b32_e32 v28, 1, v6
	global_load_dwordx4 v[160:163], v[16:17], off
	global_load_dwordx4 v[164:167], v[16:17], off offset:16
	global_load_dwordx4 v[168:171], v[16:17], off offset:32
	global_load_dwordx4 v[172:175], v[16:17], off offset:48
	global_load_dwordx4 v[176:179], v[16:17], off offset:64
	global_load_dwordx4 v[180:183], v[16:17], off offset:80
	global_load_dwordx4 v[184:187], v[16:17], off offset:96
	global_load_dwordx4 v[188:191], v[16:17], off offset:112
	s_branch .LBB0_610
; __device__ __forceinline__ unsigned cvt_pk_bf16(float lo, float hi) { unsigned r; asm volatile("v_cvt_pk_bf16_f32 %0, %1, %2" : "=v"(r) : "v"(lo), "v"(hi)); return r; }
; __device__ __forceinline__ void merge_phase(unsigned char* ws_, unsigned char* outb, const float* outg_, int wg, int nwg, int grp, int tok0, int tokend, bf16_t* obuf) {
;     ...
;         float ss = 0.f;
; #pragma unroll
;         for (int i = 0; i < 32; ++i) ss += v[i] * v[i];
;         ss += __shfl_xor(ss, 1); ss += __shfl_xor(ss, 2);
;         const float rs = __frsqrt_rn(ss * (1.0f / 128.0f) + EPS);
;         u32x4* dp = (u32x4*)(obuf + (size_t)(tok - tok0) * DM + h * 128 + q * 32);
; #pragma unroll
;         for (int c = 0; c < 4; ++c) { const f32x4 g0 = *(const f32x4*)(outg + 8 * c), g1 = *(const f32x4*)(outg + 8 * c + 4);
;             u32x4 w; w.x = cvt_pk_bf16(v[8 * c + 0] * rs * g0[0], v[8 * c + 1] * rs * g0[1]); w.y = cvt_pk_bf16(v[8 * c + 2] * rs * g0[2], v[8 * c + 3] * rs * g0[3]);
;             w.z = cvt_pk_bf16(v[8 * c + 4] * rs * g1[0], v[8 * c + 5] * rs * g1[1]); w.w = cvt_pk_bf16(v[8 * c + 6] * rs * g1[2], v[8 * c + 7] * rs * g1[3]);
;             dp[c] = w; }
.LBB0_609:
	s_or_b64 exec, exec, s[44:45]
	v_mul_f32_e32 v14, v49, v49
	v_fmac_f32_e32 v14, v48, v48
	v_fmac_f32_e32 v14, v46, v46
	v_fmac_f32_e32 v14, v47, v47
	v_fmac_f32_e32 v14, v44, v44
	v_fmac_f32_e32 v14, v45, v45
	v_fmac_f32_e32 v14, v42, v42
	v_fmac_f32_e32 v14, v43, v43
	v_fmac_f32_e32 v14, v40, v40
	v_fmac_f32_e32 v14, v41, v41
	v_fmac_f32_e32 v14, v38, v38
	v_fmac_f32_e32 v14, v39, v39
	v_fmac_f32_e32 v14, v36, v36
	v_fmac_f32_e32 v14, v37, v37
	v_fmac_f32_e32 v14, v34, v34
	v_fmac_f32_e32 v14, v35, v35
	v_fmac_f32_e32 v14, v32, v32
	v_fmac_f32_e32 v14, v33, v33
	v_fmac_f32_e32 v14, v30, v30
	v_fmac_f32_e32 v14, v31, v31
	v_fmac_f32_e32 v14, v10, v10
	v_fmac_f32_e32 v14, v11, v11
	v_fmac_f32_e32 v14, v8, v8
	v_fmac_f32_e32 v14, v9, v9
	v_fmac_f32_e32 v14, v6, v6
	v_fmac_f32_e32 v14, v7, v7
	v_fmac_f32_e32 v14, v4, v4
	v_pk_mul_f32 v[64:65], v[2:3], v[2:3]
	v_fmac_f32_e32 v14, v5, v5
	v_add_f32_e32 v14, v64, v14
	v_pk_mul_f32 v[50:51], v[0:1], v[0:1]
	v_add_f32_e32 v14, v65, v14
	v_add_f32_e32 v14, v50, v14
	v_add_f32_e32 v14, v51, v14
	ds_bpermute_b32 v27, v52, v14
	v_lshl_add_u64 v[50:51], s[16:17], 0, v[22:23]
	v_add_u32_e32 v12, s26, v12
	v_cmp_le_i32_e32 vcc, s10, v12
	v_add_u32_e32 v54, s11, v54
	s_waitcnt lgkmcnt(0)
	v_add_f32_e32 v14, v14, v27
	ds_bpermute_b32 v27, v53, v14
	v_lshl_add_u64 v[20:21], v[20:21], 0, s[8:9]
	v_lshl_add_u64 v[22:23], v[22:23], 0, s[30:31]
	s_or_b64 s[34:35], vcc, s[34:35]
	v_lshl_add_u64 v[24:25], v[24:25], 0, s[30:31]
	s_waitcnt lgkmcnt(0)
	v_add_f32_e32 v14, v14, v27
	v_fmamk_f32 v14, v14, 0x3c000000, v13
	v_rsq_f32_e32 v14, v14
	s_nop 0
	v_mul_f32_e32 v44, v44, v14
	v_mul_f32_e32 v45, v45, v14
	v_mul_f32_e32 v27, v48, v14
	v_mul_f32_e32 v29, v49, v14
	v_mul_f32_e32 v46, v46, v14
	v_mul_f32_e32 v47, v47, v14
	v_mul_f32_e32 v42, v42, v14
	v_mul_f32_e32 v43, v43, v14
	v_mul_f32_e32 v36, v36, v14
	v_mul_f32_e32 v37, v37, v14
	v_mul_f32_e32 v38, v38, v14
	v_mul_f32_e32 v39, v39, v14
	v_mul_f32_e32 v34, v34, v14
	v_mul_f32_e32 v35, v35, v14
	v_mul_f32_e32 v10, v10, v14
	v_mul_f32_e32 v11, v11, v14
	v_mul_f32_e32 v30, v30, v14
	v_mul_f32_e32 v31, v31, v14
	v_mul_f32_e32 v8, v8, v14
	v_mul_f32_e32 v9, v9, v14
	v_mul_f32_e32 v2, v2, v14
	v_mul_f32_e32 v3, v3, v14
	v_mul_f32_e32 v6, v6, v14
	v_mul_f32_e32 v7, v7, v14
	v_mul_f32_e32 v4, v4, v14
	v_mul_f32_e32 v5, v5, v14
	v_mul_f32_e32 v0, v0, v14
	v_mul_f32_e32 v27, v160, v27
	v_mul_f32_e32 v44, v164, v44
	v_mul_f32_e32 v45, v165, v45
	v_mul_f32_e32 v29, v161, v29
	v_mul_f32_e32 v46, v162, v46
	v_mul_f32_e32 v47, v163, v47
	v_mul_f32_e32 v48, v166, v42
	v_mul_f32_e32 v49, v167, v43
	v_cvt_pk_bf16_f32 v42, v27, v29
	v_cvt_pk_bf16_f32 v43, v46, v47
	v_cvt_pk_bf16_f32 v44, v44, v45
	v_cvt_pk_bf16_f32 v45, v48, v49
	global_store_dwordx4 v[50:51], v[42:45], off offset:-32
	v_mul_f32_e32 v27, v40, v14
	v_mul_f32_e32 v29, v41, v14
	v_mul_f32_e32 v1, v1, v14
	v_mul_f32_e32 v27, v168, v27
	v_mul_f32_e32 v36, v172, v36
	v_mul_f32_e32 v37, v173, v37
	v_mul_f32_e32 v29, v169, v29
	v_mul_f32_e32 v38, v170, v38
	v_mul_f32_e32 v39, v171, v39
	v_mul_f32_e32 v40, v174, v34
	v_mul_f32_e32 v41, v175, v35
	v_cvt_pk_bf16_f32 v34, v27, v29
	v_cvt_pk_bf16_f32 v35, v38, v39
	v_cvt_pk_bf16_f32 v36, v36, v37
	v_cvt_pk_bf16_f32 v37, v40, v41
	global_store_dwordx4 v[50:51], v[34:37], off offset:-16
	v_mul_f32_e32 v27, v32, v14
	v_mul_f32_e32 v29, v33, v14
	v_mul_f32_e32 v27, v176, v27
	v_mul_f32_e32 v10, v180, v10
	v_mul_f32_e32 v11, v181, v11
	v_mul_f32_e32 v29, v177, v29
	v_mul_f32_e32 v30, v178, v30
	v_mul_f32_e32 v31, v179, v31
	v_mul_f32_e32 v32, v182, v8
	v_mul_f32_e32 v33, v183, v9
	v_cvt_pk_bf16_f32 v8, v27, v29
	v_cvt_pk_bf16_f32 v9, v30, v31
	v_cvt_pk_bf16_f32 v10, v10, v11
	v_cvt_pk_bf16_f32 v11, v32, v33
	global_store_dwordx4 v[50:51], v[8:11], off
	v_mul_f32_e32 v6, v184, v6
	v_mul_f32_e32 v2, v188, v2
	v_mul_f32_e32 v3, v189, v3
	v_mul_f32_e32 v7, v185, v7
	v_mul_f32_e32 v4, v186, v4
	v_mul_f32_e32 v5, v187, v5
	v_mul_f32_e32 v8, v190, v0
	v_mul_f32_e32 v9, v191, v1
	v_cvt_pk_bf16_f32 v0, v6, v7
	v_cvt_pk_bf16_f32 v1, v4, v5
	v_cvt_pk_bf16_f32 v2, v2, v3
	v_cvt_pk_bf16_f32 v3, v8, v9
	global_store_dwordx4 v[50:51], v[0:3], off offset:16
	s_andn2_b64 exec, exec, s[34:35]
	s_cbranch_execz .LBB0_614
